# steady steps: the three LDS-DMAs issued at the end of the step; all next-tile C-operand inits as scalar v_fma instead of v_pk_fma
# baseline (speedup 1.0000x reference)
; #define WAIT_BAR(N) asm volatile("s_waitcnt vmcnt(" #N ") lgkmcnt(0)\n\ts_barrier":::"memory")
;   #define DMA_K(t,slot) glds16(ksrc+(long)(t)*KVBLK*PIN,(unsigned)__builtin_amdgcn_readfirstlane(kdst+(slot)))
;   #define DMA_V(t,slot) glds16(vsrc+(long)(t)*KVBLK*PIN,(unsigned)__builtin_amdgcn_readfirstlane(vdst+(slot)))
;   #define CINIT(C0,C1,btl) do{ const float b_=(btl); _Pragma("unroll") for(int r=0;r<16;++r){ C0[r]=__builtin_fmaf(s2,(float)((r&3)+8*(r>>2)),b_); C1[r]=__builtin_fmaf(s2,(float)((r&3)+8*(r>>2)+32),b_);} }while(0)
;   #define CMASK(P0,P1,t) do{ if(WIN||(t)>=NT-4)gmask(P0,P1,64*(t),qrel,hi,WIN);}while(0)
;   #define START(P0,P1) do{ resc=false; \
;     if(!NOMAX){ const float rm=rowmax(P0,P1); const float dl=__builtin_fmaxf(rm,0.f);     \
;       mhat=fadd_s(mhat,dl); \
;       _Pragma("unroll") for(int r=0;r<16;++r){P0[r]=fsub_s(P0[r],dl);P1[r]=fsub_s(P1[r],dl);} } \
;     _Pragma("unroll") for(int r=0;r<16;++r)P0[r]=__builtin_amdgcn_exp2f(P0[r]); }while(0)
;   #define ROT() do{sl_prev=sl_cur;sl_cur=sl_next;sl_next=(sl_next==(NSLOT-1)*SLOTB)?0:sl_next+SLOTB;}while(0)
;   #define CMASK(P0,P1,t) do{}while(0)
;   #define CMASK(P0,P1,t) do{ if(WIN||(t)>=NT-4)gmask(P0,P1,64*(t),qrel,hi,WIN);}while(0)
; template<int THRL> __device__ __forceinline__ void attn_unit(long rowbase,int qb,int t0,bool WIN,bool NOMAX,const bf16*Qc,const bf16*__restrict__ Kc,const bf16*__restrict__ Vc,bf16*Oc,float s2,float sink2,char*shm,
;     bf16x8 (&qr)[4],bool pref,const bf16*qkvb,int vn,int in_){
;     ...
;   CINIT(pA0,pA1,-qb2); qkt(pA0,pA1,Kbase,qr,r32,hi);asm volatile("s_nop 15\n\ts_nop 7":"+v"(pA0),"+v"(pA1));CMASK(pA0,pA1,0);
;   START(pA0,pA1);
;   _Pragma("unroll") for(int r=0;r<16;++r)pA1[r]=__builtin_amdgcn_exp2f(pA1[r]);
;   WAIT_BAR(0);
;   DMA_K(3,0);DMA_V(1,SLOTB);
;   ROT();
;   kload8(kf,kp0+sl_cur);
;   CINIT(pB0,pB1,__builtin_fmaf(s2,64.f,-qb2)-mhat); asm volatile("":"+v"(pB0)); asm volatile("":"+v"(pB1));
;   WAIT_BAR(2);
;   s16x4 vlo[8],vhi[8]; u32x4 pw0,pw1,pw2,pw3;
.LBB0_332:
	s_or_b64 exec, exec, s[42:43]
	s_and_b32 s42, s44, 0x3fffffc0
	s_lshl_b32 s42, s42, 2
	s_add_i32 s44, s42, 0
	s_waitcnt vmcnt(0) lgkmcnt(0)
	s_barrier
	s_mov_b64 s[64:65], 0xd8000
	v_exp_f32_e32 v114, v18
	v_exp_f32_e32 v115, v19
	v_lshl_add_u64 v[18:19], v[194:195], 0, s[64:65]
	s_mov_b32 s42, m0
	s_mov_b32 m0, s50
	s_nop 0
	global_load_lds_dwordx4 v[18:19], off
	s_mov_b32 m0, s42
	s_cmp_lg_u32 0, -1
	s_cselect_b32 s42, 0, 0
	s_add_i32 s42, s42, s82
	v_lshl_add_u64 v[192:193], v[82:83], 0, s[6:7]
	s_add_i32 s42, s42, 0x8000
	s_mov_b32 s43, m0
	s_mov_b32 m0, s42
	s_nop 0
	global_load_lds_dwordx4 v[192:193], off
	s_add_i32 m0, s42, 0xe780
	s_nop 0
	global_load_lds_dwordx4 v[192:193], off offset:128
	s_mov_b32 m0, s43
	ds_read_b128 v[174:177], v231 offset:8192
	ds_read_b128 v[170:173], v231 offset:8704
	ds_read_b128 v[166:169], v231 offset:10240
	ds_read_b128 v[162:165], v231 offset:10752
	ds_read_b128 v[158:161], v231 offset:12288
	ds_read_b128 v[154:157], v231 offset:12800
	ds_read_b128 v[150:153], v231 offset:14336
	ds_read_b128 v[146:149], v231 offset:14848
	v_lshlrev_b32_e32 v51, 1, v50
	v_lshrrev_b32_e32 v50, 2, v50
	v_and_b32_e32 v229, 32, v51
	v_and_or_b32 v50, v50, 3, v230
	v_fmamk_f32 v18, v184, 0x42800000, v186
	v_lshlrev_b32_e32 v226, 6, v50
	v_add_u32_e32 v50, 0, v229
	v_sub_f32_e32 v18, v18, v225
	v_mov_b32_e32 v185, v184
	v_add3_u32 v232, v50, v219, v226
	v_exp_f32_e32 v116, v20
	v_exp_f32_e32 v117, v21
	v_exp_f32_e32 v118, v22
	v_exp_f32_e32 v119, v23
	v_exp_f32_e32 v120, v24
	v_exp_f32_e32 v121, v25
	v_exp_f32_e32 v122, v26
	v_exp_f32_e32 v123, v27
	v_exp_f32_e32 v124, v28
	v_exp_f32_e32 v125, v29
	v_exp_f32_e32 v126, v30
	v_exp_f32_e32 v127, v31
	v_exp_f32_e32 v128, v32
	v_exp_f32_e32 v129, v33
	v_exp_f32_e32 v98, v34
	v_exp_f32_e32 v99, v35
	v_exp_f32_e32 v100, v36
	v_exp_f32_e32 v101, v37
	v_exp_f32_e32 v102, v38
	v_exp_f32_e32 v103, v39
	v_exp_f32_e32 v104, v40
	v_exp_f32_e32 v105, v41
	v_exp_f32_e32 v106, v42
	v_exp_f32_e32 v107, v43
	v_exp_f32_e32 v108, v44
	v_exp_f32_e32 v109, v45
	v_exp_f32_e32 v110, v46
	v_exp_f32_e32 v111, v47
	v_exp_f32_e32 v112, v48
	v_exp_f32_e32 v113, v49
	v_fma_f32 v66, 0, v184, v18
	v_add_f32_e32 v67, v184, v18
	v_fma_f32 v69, v191, s9, v18
	v_fma_f32 v68, v190, s8, v18
	v_fma_f32 v71, v191, s11, v18
	v_fma_f32 v70, v190, s10, v18
	v_fma_f32 v73, v191, s13, v18
	v_fma_f32 v72, v190, s12, v18
	v_fma_f32 v75, v191, s15, v18
	v_fma_f32 v74, v190, s14, v18
	v_fma_f32 v77, v191, s17, v18
	v_fma_f32 v76, v190, s16, v18
	v_fma_f32 v79, v191, s19, v18
	v_fma_f32 v78, v190, s18, v18
	v_fma_f32 v81, v191, s21, v18
	v_fma_f32 v80, v190, s20, v18
	v_fma_f32 v65, v185, s23, v18
	v_fma_f32 v64, v184, s22, v18
	v_fma_f32 v63, v185, s25, v18
	v_fma_f32 v62, v184, s24, v18
	v_fma_f32 v61, v185, s27, v18
	v_fma_f32 v60, v184, s26, v18
	v_fma_f32 v59, v185, s29, v18
	v_fma_f32 v58, v184, s28, v18
	v_fma_f32 v57, v185, s31, v18
	v_fma_f32 v56, v184, s30, v18
	v_fma_f32 v55, v185, s35, v18
	v_fma_f32 v54, v184, s34, v18
	v_fma_f32 v53, v185, s37, v18
	v_fma_f32 v52, v184, s36, v18
	v_fma_f32 v51, v189, s93, v18
	v_fma_f32 v50, v188, s92, v18
	s_mov_b32 s67, 1
	s_waitcnt vmcnt(3) lgkmcnt(0)
	s_barrier
	v_mov_b32_e32 v236, 0
	v_mov_b32_e32 v237, 0
	v_mov_b32_e32 v238, 0
	v_mov_b32_e32 v239, 0
	v_mov_b32_e32 v240, 0
	v_mov_b32_e32 v241, 0
	v_mov_b32_e32 v242, 0
	v_mov_b32_e32 v243, 0
	v_mov_b32_e32 v244, 0
	v_mov_b32_e32 v245, 0
	v_mov_b32_e32 v246, 0
	v_mov_b32_e32 v247, 0
	v_mov_b32_e32 v248, 0
	v_mov_b32_e32 v249, 0
	v_mov_b32_e32 v250, 0
	v_mov_b32_e32 v251, 0
	v_mov_b32_e32 v200, 0
	v_mov_b32_e32 v201, 0
	v_mov_b32_e32 v202, 0
	v_mov_b32_e32 v203, 0
	v_mov_b32_e32 v204, 0
	v_mov_b32_e32 v205, 0
	v_mov_b32_e32 v206, 0
	v_mov_b32_e32 v207, 0
	v_mov_b32_e32 v208, 0
	v_mov_b32_e32 v209, 0
	v_mov_b32_e32 v210, 0
	v_mov_b32_e32 v211, 0
	v_mov_b32_e32 v212, 0
	v_mov_b32_e32 v213, 0
	v_mov_b32_e32 v214, 0
	v_mov_b32_e32 v215, 0
	s_mov_b32 s66, 0
	s_cmp_lt_i32 s4, 7
	v_cmp_gt_u32_e64 s[42:43], 32, v183
	v_lshl_add_u32 v228, v180, 2, s44
	v_lshl_add_u32 v227, v230, 2, s44
	s_cbranch_scc1 .LBB0_355
	v_mov_b32_e32 v32, v1
	v_mov_b32_e32 v33, v1
	s_mov_b64 s[44:45], 0x168000
	v_mov_b32_e32 v18, v1
	v_mov_b32_e32 v19, v1
	v_mov_b32_e32 v20, v1
	v_mov_b32_e32 v21, v1
	v_mov_b32_e32 v22, v1
	v_mov_b32_e32 v23, v1
	v_mov_b32_e32 v24, v1
	v_mov_b32_e32 v25, v1
	v_mov_b32_e32 v26, v1
	v_mov_b32_e32 v27, v1
	v_mov_b32_e32 v28, v1
	v_mov_b32_e32 v29, v1
	v_mov_b32_e32 v30, v1
	v_mov_b32_e32 v31, v1
	v_mov_b64_e32 v[48:49], v[32:33]
	s_add_i32 s48, s4, -5
	v_lshl_add_u64 v[196:197], v[82:83], 0, s[64:65]
	v_lshl_add_u64 v[198:199], v[194:195], 0, s[44:45]
	s_mov_b32 s44, 0
	s_movk_i32 s66, 0x4000
	s_movk_i32 s51, 0x2000
	v_mov_b32_e32 v82, 0
	s_movk_i32 s49, 0xc0
	v_mov_b64_e32 v[46:47], v[30:31]
	v_mov_b64_e32 v[44:45], v[28:29]
	v_mov_b64_e32 v[42:43], v[26:27]
	v_mov_b64_e32 v[40:41], v[24:25]
	v_mov_b64_e32 v[38:39], v[22:23]
	v_mov_b64_e32 v[36:37], v[20:21]
	v_mov_b64_e32 v[34:35], v[18:19]
.LBB0_334:
	v_add_u32_e32 v83, s44, v232
	v_add_u32_e32 v255, 0xe800, v83
	ds_read_b64_tr_b16 v[84:85], v83 offset:24576
	ds_read_b64_tr_b16 v[86:87], v83 offset:25088
	s_waitcnt lgkmcnt(9)
	v_mfma_f32_32x32x16_bf16 v[66:81], v[174:177], v[2:5], v[66:81]
	v_add_f32_e32 v88, v114, v115
	v_add_f32_e32 v88, v116, v88
	v_add_f32_e32 v88, v117, v88
	v_add_f32_e32 v88, v118, v88
	v_add_f32_e32 v92, v119, v88
	v_cvt_pk_bf16_f32 v142, v114, v115
	v_cvt_pk_bf16_f32 v143, v116, v117
	ds_read_b64_tr_b16 v[88:89], v83 offset:28672
	ds_read_b64_tr_b16 v[90:91], v83 offset:29184
	s_waitcnt lgkmcnt(10)
	v_mfma_f32_32x32x16_bf16 v[50:65], v[170:173], v[2:5], v[50:65]
	v_add_f32_e32 v92, v120, v92
	v_add_f32_e32 v92, v121, v92
	v_add_f32_e32 v92, v122, v92
	v_add_f32_e32 v96, v123, v92
	v_cvt_pk_bf16_f32 v144, v118, v119
	v_cvt_pk_bf16_f32 v145, v120, v121
	ds_read_b64_tr_b16 v[92:93], v83 offset:25600
	ds_read_b64_tr_b16 v[94:95], v83 offset:26112
	s_waitcnt lgkmcnt(11)
	v_mfma_f32_32x32x16_bf16 v[66:81], v[166:169], v[6:9], v[66:81]
	v_add_f32_e32 v96, v124, v96
	v_add_f32_e32 v96, v125, v96
	v_add_f32_e32 v96, v126, v96
	v_add_f32_e32 v96, v127, v96
	v_cvt_pk_bf16_f32 v138, v122, v123
	v_cvt_pk_bf16_f32 v139, v124, v125
	ds_read_b64_tr_b16 v[114:115], v83 offset:29696
	ds_read_b64_tr_b16 v[116:117], v83 offset:30208
	s_waitcnt lgkmcnt(12)
	v_mfma_f32_32x32x16_bf16 v[50:65], v[162:165], v[6:9], v[50:65]
	v_add_f32_e32 v96, v128, v96
	v_add_f32_e32 v96, v129, v96
	v_add_f32_e32 v96, v98, v96
	v_add_f32_e32 v96, v99, v96
	v_cvt_pk_bf16_f32 v140, v126, v127
	v_cvt_pk_bf16_f32 v141, v128, v129
	ds_read_b64_tr_b16 v[118:119], v83 offset:26624
	ds_read_b64_tr_b16 v[120:121], v83 offset:27136
	s_waitcnt lgkmcnt(13)
	v_mfma_f32_32x32x16_bf16 v[66:81], v[158:161], v[10:13], v[66:81]
	v_add_f32_e32 v96, v100, v96
	v_add_f32_e32 v96, v101, v96
	v_add_f32_e32 v96, v102, v96
	v_add_f32_e32 v96, v103, v96
	v_cvt_pk_bf16_f32 v134, v98, v99
	v_cvt_pk_bf16_f32 v135, v100, v101
	ds_read_b64_tr_b16 v[98:99], v83 offset:30720
	ds_read_b64_tr_b16 v[100:101], v83 offset:31232
	s_waitcnt lgkmcnt(14)
	v_mfma_f32_32x32x16_bf16 v[50:65], v[154:157], v[10:13], v[50:65]
	v_add_f32_e32 v96, v104, v96
	v_add_f32_e32 v96, v105, v96
	v_add_f32_e32 v96, v106, v96
	v_add_f32_e32 v96, v107, v96
	v_cvt_pk_bf16_f32 v136, v102, v103
	v_cvt_pk_bf16_f32 v137, v104, v105
	ds_read_b64_tr_b16 v[102:103], v83 offset:27648
	ds_read_b64_tr_b16 v[104:105], v83 offset:28160
	s_waitcnt lgkmcnt(14)
	v_mfma_f32_32x32x16_bf16 v[66:81], v[150:153], v[14:17], v[66:81]
	v_add_f32_e32 v96, v108, v96
	v_add_f32_e32 v96, v109, v96
	v_add_f32_e32 v96, v110, v96
	v_add_f32_e32 v96, v111, v96
	v_cvt_pk_bf16_f32 v130, v106, v107
	v_cvt_pk_bf16_f32 v131, v108, v109
	ds_read_b64_tr_b16 v[106:107], v83 offset:31744
	ds_read_b64_tr_b16 v[108:109], v83 offset:32256
	v_mfma_f32_32x32x16_bf16 v[50:65], v[146:149], v[14:17], v[50:65]
	v_add_f32_e32 v83, v112, v96
	v_add_f32_e32 v83, v113, v83
	v_add_f32_e32 v83, 0, v83
	v_cvt_pk_bf16_f32 v132, v110, v111
	v_cvt_pk_bf16_f32 v133, v112, v113
	s_nop 0
	v_add_f32_e32 v166, v82, v83
	s_mov_b64 s[44:45], 0
	s_and_saveexec_b64 s[64:65], s[40:41]
	s_cbranch_execz .LBB0_337
	v_max_f32_e32 v82, v67, v67
	v_max_f32_e32 v83, v66, v66
	v_max_f32_e32 v82, v83, v82
	v_max3_f32 v83, v68, v69, v51
	v_max3_f32 v82, v82, v50, v52
	v_max3_f32 v82, v82, v53, v70
	v_max3_f32 v83, v83, v72, v73
	v_max3_f32 v82, v82, v71, v54
	v_max3_f32 v83, v83, v56, v57
	v_max3_f32 v82, v82, v55, v74
	v_max3_f32 v83, v83, v76, v77
	v_max3_f32 v82, v82, v75, v58
	v_max3_f32 v83, v83, v60, v61
	v_max3_f32 v82, v82, v59, v78
	v_max3_f32 v83, v83, v80, v81
	v_max3_f32 v82, v82, v79, v62
	v_max3_f32 v83, v83, v64, v65
	v_max3_f32 v82, v82, v63, v83
	v_mov_b32_e32 v83, v82
	s_nop 1
	v_permlane32_swap_b32_e32 v82, v83
	v_max_f32_e32 v83, v83, v83
	v_max_f32_e32 v82, v82, v82
	v_max_f32_e32 v82, v82, v83
	v_cmp_lt_f32_e32 vcc, s84, v82
	s_cbranch_vccnz .LBB0_346

.LBB0_337:
	s_or_b64 exec, exec, s[64:65]
	s_waitcnt lgkmcnt(14)
	v_mfma_f32_32x32x16_bf16 v[18:33], v[142:145], v[84:87], v[18:33]
	v_exp_f32_e32 v66, v66
	v_exp_f32_e32 v67, v67
	s_waitcnt lgkmcnt(12)
	v_mfma_f32_32x32x16_bf16 v[34:49], v[142:145], v[88:91], v[34:49]
	v_exp_f32_e32 v68, v68
	v_exp_f32_e32 v69, v69
	v_add_u32_e32 v82, s66, v231
	ds_read_b128 v[162:165], v82
	ds_read_b128 v[158:161], v82 offset:512
	s_waitcnt lgkmcnt(12)
	v_mfma_f32_32x32x16_bf16 v[18:33], v[138:141], v[92:95], v[18:33]
	v_exp_f32_e32 v70, v70
	v_exp_f32_e32 v71, v71
	ds_read_b128 v[154:157], v82 offset:2048
	ds_read_b128 v[146:149], v82 offset:2560
	s_waitcnt lgkmcnt(12)
	v_mfma_f32_32x32x16_bf16 v[34:49], v[138:141], v[114:117], v[34:49]
	v_exp_f32_e32 v72, v72
	v_exp_f32_e32 v73, v73
	ds_read_b128 v[94:97], v82 offset:4096
	ds_read_b128 v[90:93], v82 offset:4608
	s_waitcnt lgkmcnt(12)
	v_mfma_f32_32x32x16_bf16 v[18:33], v[134:137], v[118:121], v[18:33]
	v_exp_f32_e32 v74, v74
	v_exp_f32_e32 v75, v75
	ds_read_b128 v[86:89], v82 offset:6144
	ds_read_b128 v[82:85], v82 offset:6656
	s_waitcnt lgkmcnt(12)
	v_mfma_f32_32x32x16_bf16 v[34:49], v[134:137], v[98:101], v[34:49]
	v_exp_f32_e32 v76, v76
	v_exp_f32_e32 v77, v77
	s_waitcnt lgkmcnt(10)
	v_mfma_f32_32x32x16_bf16 v[18:33], v[130:133], v[102:105], v[18:33]
	v_exp_f32_e32 v78, v78
	v_exp_f32_e32 v79, v79
	s_waitcnt lgkmcnt(8)
	v_mfma_f32_32x32x16_bf16 v[34:49], v[130:133], v[106:109], v[34:49]
	v_exp_f32_e32 v80, v80
	v_exp_f32_e32 v81, v81
	ds_read_b64_tr_b16 v[98:99], v255 offset:24576
	ds_read_b64_tr_b16 v[100:101], v255 offset:25088
	ds_read_b64_tr_b16 v[102:103], v255 offset:28672
	ds_read_b64_tr_b16 v[104:105], v255 offset:29184
	ds_read_b64_tr_b16 v[106:107], v255 offset:25600
	ds_read_b64_tr_b16 v[108:109], v255 offset:26112
	ds_read_b64_tr_b16 v[110:111], v255 offset:29696
	ds_read_b64_tr_b16 v[112:113], v255 offset:30208
	ds_read_b64_tr_b16 v[114:115], v255 offset:26624
	ds_read_b64_tr_b16 v[116:117], v255 offset:27136
	ds_read_b64_tr_b16 v[118:119], v255 offset:30720
	ds_read_b64_tr_b16 v[120:121], v255 offset:31232
	ds_read_b64_tr_b16 v[122:123], v255 offset:27648
	ds_read_b64_tr_b16 v[124:125], v255 offset:28160
	ds_read_b64_tr_b16 v[126:127], v255 offset:31744
	ds_read_b64_tr_b16 v[128:129], v255 offset:32256
	s_sub_i32 s64, s49, 64
	v_exp_f32_e32 v50, v50
	v_exp_f32_e32 v51, v51
	v_exp_f32_e32 v52, v52
	v_exp_f32_e32 v53, v53
	v_exp_f32_e32 v54, v54
	v_exp_f32_e32 v55, v55
	v_exp_f32_e32 v56, v56
	v_exp_f32_e32 v57, v57
	s_waitcnt lgkmcnt(14)
	v_mfma_f32_32x32x16_bf16 v[236:251], v[142:145], v[98:101], v[236:251]
	v_cvt_f32_u32_e32 v98, s64
	v_mov_b32_e32 v185, v184
	v_fma_f32 v98, v184, v98, v186
	v_sub_f32_e32 v98, v98, v225
	v_exp_f32_e32 v58, v58
	s_waitcnt lgkmcnt(12)
	v_mfma_f32_32x32x16_bf16 v[200:215], v[142:145], v[102:105], v[200:215]
	v_fma_f32 v105, v185, s31, v98
	v_fma_f32 v104, v184, s30, v98
	v_fma_f32 v103, v185, s35, v98
	v_fma_f32 v102, v184, s34, v98
	v_exp_f32_e32 v59, v59
	s_waitcnt lgkmcnt(10)
	v_mfma_f32_32x32x16_bf16 v[236:251], v[138:141], v[106:109], v[236:251]
	v_fma_f32 v109, v185, s27, v98
	v_fma_f32 v108, v184, s26, v98
	v_fma_f32 v107, v185, s29, v98
	v_fma_f32 v106, v184, s28, v98
	v_exp_f32_e32 v60, v60
	s_waitcnt lgkmcnt(8)
	v_mfma_f32_32x32x16_bf16 v[200:215], v[138:141], v[110:113], v[200:215]
	v_fma_f32 v113, v185, s23, v98
	v_fma_f32 v112, v184, s22, v98
	v_fma_f32 v111, v185, s25, v98
	v_fma_f32 v110, v184, s24, v98
	v_exp_f32_e32 v61, v61
	s_waitcnt lgkmcnt(6)
	v_mfma_f32_32x32x16_bf16 v[236:251], v[134:137], v[114:117], v[236:251]
	v_fma_f32 v114, 0, v184, v98
	v_add_f32_e32 v115, v184, v98
	v_fma_f32 v117, v191, s9, v98
	v_fma_f32 v116, v190, s8, v98
	v_exp_f32_e32 v62, v62
	s_waitcnt lgkmcnt(4)
	v_mfma_f32_32x32x16_bf16 v[200:215], v[134:137], v[118:121], v[200:215]
	v_fma_f32 v119, v191, s11, v98
	v_fma_f32 v118, v190, s10, v98
	v_fma_f32 v121, v191, s13, v98
	v_fma_f32 v120, v190, s12, v98
	v_exp_f32_e32 v63, v63
	s_waitcnt lgkmcnt(2)
	v_mfma_f32_32x32x16_bf16 v[236:251], v[130:133], v[122:125], v[236:251]
	v_fma_f32 v123, v191, s15, v98
	v_fma_f32 v122, v190, s14, v98
	v_fma_f32 v125, v191, s17, v98
	v_fma_f32 v124, v190, s16, v98
	v_exp_f32_e32 v64, v64
	s_waitcnt lgkmcnt(0)
	v_mfma_f32_32x32x16_bf16 v[200:215], v[130:133], v[126:129], v[200:215]
	v_fma_f32 v127, v191, s19, v98
	v_fma_f32 v126, v190, s18, v98
	v_fma_f32 v129, v191, s21, v98
	v_fma_f32 v128, v190, s20, v98
	v_exp_f32_e32 v65, v65
	v_fma_f32 v101, v185, s37, v98
	v_fma_f32 v100, v184, s36, v98
	v_fma_f32 v99, v189, s93, v98
	v_fma_f32 v98, v188, s92, v98
	v_lshl_add_u64 v[130:131], v[198:199], 0, s[94:95]
	s_add_i32 s100, s51, s50
	s_mov_b32 s101, m0
	s_mov_b32 m0, s100
	s_nop 0
	global_load_lds_dwordx4 v[130:131], off
	v_lshl_add_u64 v[130:131], v[196:197], 0, s[94:95]
	s_add_i32 s100, s66, s79
	s_mov_b32 m0, s100
	s_nop 0
	global_load_lds_dwordx4 v[130:131], off
	s_add_i32 m0, s100, 0xe780
	s_nop 0
	global_load_lds_dwordx4 v[130:131], off offset:128
	s_mov_b32 m0, s101
	s_nop 0
	s_waitcnt vmcnt(3) lgkmcnt(0)
	s_barrier
	s_and_saveexec_b64 s[64:65], s[44:45]
	s_cbranch_execz .LBB0_339
	s_waitcnt lgkmcnt(0)
	ds_read_b128 v[150:153], v227 offset:49248
	ds_read_b128 v[168:171], v227 offset:49216
	ds_read_b128 v[172:175], v227 offset:49184
	s_waitcnt lgkmcnt(2)
	v_pk_mul_f32 v[32:33], v[32:33], v[152:153]
	v_pk_mul_f32 v[30:31], v[30:31], v[150:151]
	v_pk_mul_f32 v[48:49], v[48:49], v[152:153]
	v_pk_mul_f32 v[46:47], v[46:47], v[150:151]
	v_pk_mul_f32 v[250:251], v[250:251], v[152:153]
	v_pk_mul_f32 v[248:249], v[248:249], v[150:151]
	v_pk_mul_f32 v[214:215], v[214:215], v[152:153]
	v_pk_mul_f32 v[212:213], v[212:213], v[150:151]
	ds_read_b128 v[150:153], v227 offset:49152
	s_waitcnt lgkmcnt(2)
	v_pk_mul_f32 v[28:29], v[28:29], v[170:171]
	v_pk_mul_f32 v[26:27], v[26:27], v[168:169]
	v_pk_mul_f32 v[44:45], v[44:45], v[170:171]
	v_pk_mul_f32 v[42:43], v[42:43], v[168:169]
	v_pk_mul_f32 v[246:247], v[246:247], v[170:171]
	v_pk_mul_f32 v[244:245], v[244:245], v[168:169]
	v_pk_mul_f32 v[210:211], v[210:211], v[170:171]
	v_pk_mul_f32 v[208:209], v[208:209], v[168:169]
	s_waitcnt lgkmcnt(1)
	v_pk_mul_f32 v[24:25], v[24:25], v[174:175]
	v_pk_mul_f32 v[22:23], v[22:23], v[172:173]
	v_pk_mul_f32 v[40:41], v[40:41], v[174:175]
	v_pk_mul_f32 v[38:39], v[38:39], v[172:173]
	v_pk_mul_f32 v[242:243], v[242:243], v[174:175]
	v_pk_mul_f32 v[240:241], v[240:241], v[172:173]
	v_pk_mul_f32 v[206:207], v[206:207], v[174:175]
	v_pk_mul_f32 v[204:205], v[204:205], v[172:173]
	s_waitcnt lgkmcnt(0)
	v_pk_mul_f32 v[20:21], v[20:21], v[152:153]
	v_pk_mul_f32 v[18:19], v[18:19], v[150:151]
	v_pk_mul_f32 v[36:37], v[36:37], v[152:153]
	v_pk_mul_f32 v[34:35], v[34:35], v[150:151]
	v_pk_mul_f32 v[238:239], v[238:239], v[152:153]
	v_pk_mul_f32 v[236:237], v[236:237], v[150:151]
	v_pk_mul_f32 v[202:203], v[202:203], v[152:153]
	v_pk_mul_f32 v[200:201], v[200:201], v[150:151]
.LBB0_339:
	s_or_b64 exec, exec, s[64:65]
	s_add_i32 s44, s66, 0x2000
	s_cmpk_lg_i32 s66, 0x4000
	s_cselect_b32 s86, s44, 0
	v_add_u32_e32 v167, s51, v232
	v_add_u32_e32 v255, 0xe800, v167
	ds_read_b64_tr_b16 v[150:151], v167 offset:24576
	ds_read_b64_tr_b16 v[152:153], v167 offset:25088
	s_waitcnt lgkmcnt(9)
	v_mfma_f32_32x32x16_bf16 v[114:129], v[162:165], v[2:5], v[114:129]
	v_add_f32_e32 v130, v66, v67
	v_add_f32_e32 v130, v68, v130
	v_add_f32_e32 v130, v69, v130
	v_add_f32_e32 v130, v70, v130
	v_add_f32_e32 v130, v71, v130
	v_cvt_pk_bf16_f32 v142, v66, v67
	v_cvt_pk_bf16_f32 v143, v68, v69
	ds_read_b64_tr_b16 v[66:67], v167 offset:28672
	ds_read_b64_tr_b16 v[68:69], v167 offset:29184
	s_waitcnt lgkmcnt(10)
	v_mfma_f32_32x32x16_bf16 v[98:113], v[158:161], v[2:5], v[98:113]
	v_add_f32_e32 v130, v72, v130
	v_add_f32_e32 v130, v73, v130
	v_add_f32_e32 v130, v74, v130
	v_add_f32_e32 v130, v75, v130
	v_cvt_pk_bf16_f32 v144, v70, v71
	v_cvt_pk_bf16_f32 v145, v72, v73
	ds_read_b64_tr_b16 v[70:71], v167 offset:25600
	ds_read_b64_tr_b16 v[72:73], v167 offset:26112
	s_waitcnt lgkmcnt(11)
	v_mfma_f32_32x32x16_bf16 v[114:129], v[154:157], v[6:9], v[114:129]
	v_add_f32_e32 v130, v76, v130
	v_add_f32_e32 v130, v77, v130
	v_add_f32_e32 v130, v78, v130
	v_add_f32_e32 v130, v79, v130
	v_cvt_pk_bf16_f32 v138, v74, v75
	v_cvt_pk_bf16_f32 v139, v76, v77
	ds_read_b64_tr_b16 v[74:75], v167 offset:29696
	ds_read_b64_tr_b16 v[76:77], v167 offset:30208
	s_waitcnt lgkmcnt(12)
	v_mfma_f32_32x32x16_bf16 v[98:113], v[146:149], v[6:9], v[98:113]
	v_add_f32_e32 v130, v80, v130
	v_add_f32_e32 v130, v81, v130
	v_add_f32_e32 v130, v50, v130
	v_add_f32_e32 v130, v51, v130
	v_cvt_pk_bf16_f32 v140, v78, v79
	v_cvt_pk_bf16_f32 v141, v80, v81
	ds_read_b64_tr_b16 v[78:79], v167 offset:26624
	ds_read_b64_tr_b16 v[80:81], v167 offset:27136
	s_waitcnt lgkmcnt(13)
	v_mfma_f32_32x32x16_bf16 v[114:129], v[94:97], v[10:13], v[114:129]
	v_add_f32_e32 v94, v52, v130
	v_add_f32_e32 v94, v53, v94
	v_add_f32_e32 v94, v54, v94
	v_add_f32_e32 v94, v55, v94
	v_cvt_pk_bf16_f32 v134, v50, v51
	v_cvt_pk_bf16_f32 v135, v52, v53
	ds_read_b64_tr_b16 v[50:51], v167 offset:30720
	ds_read_b64_tr_b16 v[52:53], v167 offset:31232
	s_waitcnt lgkmcnt(14)
	v_mfma_f32_32x32x16_bf16 v[98:113], v[90:93], v[10:13], v[98:113]
	v_add_f32_e32 v90, v56, v94
	v_add_f32_e32 v90, v57, v90
	v_add_f32_e32 v90, v58, v90
	v_add_f32_e32 v90, v59, v90
	v_cvt_pk_bf16_f32 v136, v54, v55
	v_cvt_pk_bf16_f32 v137, v56, v57
	ds_read_b64_tr_b16 v[54:55], v167 offset:27648
	ds_read_b64_tr_b16 v[56:57], v167 offset:28160
	s_waitcnt lgkmcnt(14)
	v_mfma_f32_32x32x16_bf16 v[114:129], v[86:89], v[14:17], v[114:129]
	v_add_f32_e32 v86, v60, v90
	v_add_f32_e32 v86, v61, v86
	v_add_f32_e32 v86, v62, v86
	v_add_f32_e32 v86, v63, v86
	v_cvt_pk_bf16_f32 v130, v58, v59
	v_cvt_pk_bf16_f32 v131, v60, v61
	ds_read_b64_tr_b16 v[58:59], v167 offset:31744
	ds_read_b64_tr_b16 v[60:61], v167 offset:32256
	v_mfma_f32_32x32x16_bf16 v[98:113], v[82:85], v[14:17], v[98:113]
	v_add_f32_e32 v82, v64, v86
	v_add_f32_e32 v82, v65, v82
	v_add_f32_e32 v82, 0, v82
	v_cvt_pk_bf16_f32 v132, v62, v63
	v_cvt_pk_bf16_f32 v133, v64, v65
	v_add_f32_e32 v82, v166, v82
	s_mov_b64 s[44:45], 0
	s_and_saveexec_b64 s[64:65], s[40:41]
	s_cbranch_execz .LBB0_342
	v_max_f32_e32 v62, v115, v115
	v_max_f32_e32 v63, v114, v114
	v_max_f32_e32 v62, v63, v62
	v_max3_f32 v63, v116, v117, v99
	v_max3_f32 v62, v62, v98, v100
	v_max3_f32 v62, v62, v101, v118
	v_max3_f32 v63, v63, v120, v121
	v_max3_f32 v62, v62, v119, v102
	v_max3_f32 v63, v63, v104, v105
	v_max3_f32 v62, v62, v103, v122
	v_max3_f32 v63, v63, v124, v125
	v_max3_f32 v62, v62, v123, v106
	v_max3_f32 v63, v63, v108, v109
	v_max3_f32 v62, v62, v107, v126
	v_max3_f32 v63, v63, v128, v129
	v_max3_f32 v62, v62, v127, v110
	v_max3_f32 v63, v63, v112, v113
	v_max3_f32 v62, v62, v111, v63
	v_mov_b32_e32 v63, v62
	s_nop 1
	v_permlane32_swap_b32_e32 v62, v63
	v_max_f32_e32 v63, v63, v63
	v_max_f32_e32 v62, v62, v62
	v_max_f32_e32 v62, v62, v63
	v_cmp_lt_f32_e32 vcc, s84, v62
	s_cbranch_vccnz .LBB0_349

.LBB0_342:
	s_or_b64 exec, exec, s[64:65]
	s_waitcnt lgkmcnt(14)
	v_mfma_f32_32x32x16_bf16 v[18:33], v[142:145], v[150:153], v[18:33]
	v_exp_f32_e32 v114, v114
	v_exp_f32_e32 v115, v115
	s_waitcnt lgkmcnt(12)
	v_mfma_f32_32x32x16_bf16 v[34:49], v[142:145], v[66:69], v[34:49]
	v_exp_f32_e32 v116, v116
	v_exp_f32_e32 v117, v117
	v_add_u32_e32 v62, s86, v231
	ds_read_b128 v[174:177], v62
	ds_read_b128 v[170:173], v62 offset:512
	s_waitcnt lgkmcnt(12)
	v_mfma_f32_32x32x16_bf16 v[18:33], v[138:141], v[70:73], v[18:33]
	v_exp_f32_e32 v118, v118
	v_exp_f32_e32 v119, v119
	ds_read_b128 v[166:169], v62 offset:2048
	ds_read_b128 v[162:165], v62 offset:2560
	s_waitcnt lgkmcnt(12)
	v_mfma_f32_32x32x16_bf16 v[34:49], v[138:141], v[74:77], v[34:49]
	v_exp_f32_e32 v120, v120
	v_exp_f32_e32 v121, v121
	ds_read_b128 v[158:161], v62 offset:4096
	ds_read_b128 v[154:157], v62 offset:4608
	s_waitcnt lgkmcnt(12)
	v_mfma_f32_32x32x16_bf16 v[18:33], v[134:137], v[78:81], v[18:33]
	v_exp_f32_e32 v122, v122
	v_exp_f32_e32 v123, v123
	ds_read_b128 v[150:153], v62 offset:6144
	ds_read_b128 v[146:149], v62 offset:6656
	s_waitcnt lgkmcnt(12)
	v_mfma_f32_32x32x16_bf16 v[34:49], v[134:137], v[50:53], v[34:49]
	v_exp_f32_e32 v124, v124
	v_exp_f32_e32 v125, v125
	s_waitcnt lgkmcnt(10)
	v_mfma_f32_32x32x16_bf16 v[18:33], v[130:133], v[54:57], v[18:33]
	v_exp_f32_e32 v126, v126
	v_exp_f32_e32 v127, v127
	s_waitcnt lgkmcnt(8)
	v_mfma_f32_32x32x16_bf16 v[34:49], v[130:133], v[58:61], v[34:49]
	v_exp_f32_e32 v128, v128
	v_exp_f32_e32 v129, v129
	ds_read_b64_tr_b16 v[50:51], v255 offset:24576
	ds_read_b64_tr_b16 v[52:53], v255 offset:25088
	ds_read_b64_tr_b16 v[54:55], v255 offset:28672
	ds_read_b64_tr_b16 v[56:57], v255 offset:29184
	ds_read_b64_tr_b16 v[58:59], v255 offset:25600
	ds_read_b64_tr_b16 v[60:61], v255 offset:26112
	ds_read_b64_tr_b16 v[62:63], v255 offset:29696
	ds_read_b64_tr_b16 v[64:65], v255 offset:30208
	ds_read_b64_tr_b16 v[66:67], v255 offset:26624
	ds_read_b64_tr_b16 v[68:69], v255 offset:27136
	ds_read_b64_tr_b16 v[70:71], v255 offset:30720
	ds_read_b64_tr_b16 v[72:73], v255 offset:31232
	ds_read_b64_tr_b16 v[74:75], v255 offset:27648
	ds_read_b64_tr_b16 v[76:77], v255 offset:28160
	ds_read_b64_tr_b16 v[78:79], v255 offset:31744
	ds_read_b64_tr_b16 v[80:81], v255 offset:32256
	v_exp_f32_e32 v98, v98
	v_exp_f32_e32 v99, v99
	v_exp_f32_e32 v100, v100
	v_exp_f32_e32 v101, v101
	v_exp_f32_e32 v102, v102
	v_exp_f32_e32 v103, v103
	v_exp_f32_e32 v104, v104
	v_exp_f32_e32 v105, v105
	s_waitcnt lgkmcnt(14)
	v_mfma_f32_32x32x16_bf16 v[236:251], v[142:145], v[50:53], v[236:251]
	v_cvt_f32_u32_e32 v50, s49
	v_mov_b32_e32 v185, v184
	v_fma_f32 v50, v184, v50, v186
	v_sub_f32_e32 v50, v50, v225
	v_exp_f32_e32 v106, v106
	s_waitcnt lgkmcnt(12)
	v_mfma_f32_32x32x16_bf16 v[200:215], v[142:145], v[54:57], v[200:215]
	v_fma_f32 v57, v185, s31, v50
	v_fma_f32 v56, v184, s30, v50
	v_fma_f32 v55, v185, s35, v50
	v_fma_f32 v54, v184, s34, v50
	v_exp_f32_e32 v107, v107
	s_waitcnt lgkmcnt(10)
	v_mfma_f32_32x32x16_bf16 v[236:251], v[138:141], v[58:61], v[236:251]
	v_fma_f32 v61, v185, s27, v50
	v_fma_f32 v60, v184, s26, v50
	v_fma_f32 v59, v185, s29, v50
	v_fma_f32 v58, v184, s28, v50
	v_exp_f32_e32 v108, v108
	s_waitcnt lgkmcnt(8)
	v_mfma_f32_32x32x16_bf16 v[200:215], v[138:141], v[62:65], v[200:215]
	v_fma_f32 v65, v185, s23, v50
	v_fma_f32 v64, v184, s22, v50
	v_fma_f32 v63, v185, s25, v50
	v_fma_f32 v62, v184, s24, v50
	v_exp_f32_e32 v109, v109
	s_waitcnt lgkmcnt(6)
	v_mfma_f32_32x32x16_bf16 v[236:251], v[134:137], v[66:69], v[236:251]
	v_fma_f32 v66, 0, v184, v50
	v_add_f32_e32 v67, v184, v50
	v_fma_f32 v69, v191, s9, v50
	v_fma_f32 v68, v190, s8, v50
	v_exp_f32_e32 v110, v110
	s_waitcnt lgkmcnt(4)
	v_mfma_f32_32x32x16_bf16 v[200:215], v[134:137], v[70:73], v[200:215]
	v_fma_f32 v71, v191, s11, v50
	v_fma_f32 v70, v190, s10, v50
	v_fma_f32 v73, v191, s13, v50
	v_fma_f32 v72, v190, s12, v50
	v_exp_f32_e32 v111, v111
	s_waitcnt lgkmcnt(2)
	v_mfma_f32_32x32x16_bf16 v[236:251], v[130:133], v[74:77], v[236:251]
	v_fma_f32 v75, v191, s15, v50
	v_fma_f32 v74, v190, s14, v50
	v_fma_f32 v77, v191, s17, v50
	v_fma_f32 v76, v190, s16, v50
	v_exp_f32_e32 v112, v112
	s_waitcnt lgkmcnt(0)
	v_mfma_f32_32x32x16_bf16 v[200:215], v[130:133], v[78:81], v[200:215]
	v_fma_f32 v79, v191, s19, v50
	v_fma_f32 v78, v190, s18, v50
	v_fma_f32 v81, v191, s21, v50
	v_fma_f32 v80, v190, s20, v50
	v_exp_f32_e32 v113, v113
	v_fma_f32 v53, v185, s37, v50
	v_fma_f32 v52, v184, s36, v50
	v_fma_f32 v51, v189, s93, v50
	v_fma_f32 v50, v188, s92, v50
	s_add_i32 s100, s66, s50
	s_mov_b32 s101, m0
	s_mov_b32 m0, s100
	s_nop 0
	global_load_lds_dwordx4 v[198:199], off
	s_add_i32 s100, s86, s79
	s_mov_b32 m0, s100
	s_nop 0
	global_load_lds_dwordx4 v[196:197], off
	s_add_i32 m0, s100, 0xe780
	s_nop 0
	global_load_lds_dwordx4 v[196:197], off offset:128
	s_mov_b32 m0, s101
	s_nop 0
	s_waitcnt vmcnt(3) lgkmcnt(0)
	s_barrier
	s_and_saveexec_b64 s[64:65], s[44:45]
	s_cbranch_execz .LBB0_344
	s_waitcnt lgkmcnt(0)
	ds_read_b128 v[84:87], v227 offset:49248
	ds_read_b128 v[88:91], v227 offset:49216
	ds_read_b128 v[92:95], v227 offset:49184
	s_waitcnt lgkmcnt(2)
	v_pk_mul_f32 v[32:33], v[32:33], v[86:87]
	v_pk_mul_f32 v[30:31], v[30:31], v[84:85]
	v_pk_mul_f32 v[48:49], v[48:49], v[86:87]
	v_pk_mul_f32 v[46:47], v[46:47], v[84:85]
	v_pk_mul_f32 v[250:251], v[250:251], v[86:87]
	v_pk_mul_f32 v[248:249], v[248:249], v[84:85]
	v_pk_mul_f32 v[214:215], v[214:215], v[86:87]
	v_pk_mul_f32 v[212:213], v[212:213], v[84:85]
	ds_read_b128 v[84:87], v227 offset:49152
	s_waitcnt lgkmcnt(2)
	v_pk_mul_f32 v[28:29], v[28:29], v[90:91]
	v_pk_mul_f32 v[26:27], v[26:27], v[88:89]
	v_pk_mul_f32 v[44:45], v[44:45], v[90:91]
	v_pk_mul_f32 v[42:43], v[42:43], v[88:89]
	v_pk_mul_f32 v[246:247], v[246:247], v[90:91]
	v_pk_mul_f32 v[244:245], v[244:245], v[88:89]
	v_pk_mul_f32 v[210:211], v[210:211], v[90:91]
	v_pk_mul_f32 v[208:209], v[208:209], v[88:89]
	s_waitcnt lgkmcnt(1)
	v_pk_mul_f32 v[24:25], v[24:25], v[94:95]
	v_pk_mul_f32 v[22:23], v[22:23], v[92:93]
	v_pk_mul_f32 v[40:41], v[40:41], v[94:95]
	v_pk_mul_f32 v[38:39], v[38:39], v[92:93]
	v_pk_mul_f32 v[242:243], v[242:243], v[94:95]
	v_pk_mul_f32 v[240:241], v[240:241], v[92:93]
	v_pk_mul_f32 v[206:207], v[206:207], v[94:95]
	v_pk_mul_f32 v[204:205], v[204:205], v[92:93]
	s_waitcnt lgkmcnt(0)
	v_pk_mul_f32 v[20:21], v[20:21], v[86:87]
	v_pk_mul_f32 v[18:19], v[18:19], v[84:85]
	v_pk_mul_f32 v[36:37], v[36:37], v[86:87]
	v_pk_mul_f32 v[34:35], v[34:35], v[84:85]
	v_pk_mul_f32 v[238:239], v[238:239], v[86:87]
	v_pk_mul_f32 v[236:237], v[236:237], v[84:85]
	v_pk_mul_f32 v[202:203], v[202:203], v[86:87]
	v_pk_mul_f32 v[200:201], v[200:201], v[84:85]

.LBB0_430:
	s_or_b64 exec, exec, s[66:67]
	s_waitcnt lgkmcnt(14)
	v_mfma_f32_32x32x16_bf16 v[18:33], v[142:145], v[84:87], v[18:33]
	v_exp_f32_e32 v66, v66
	v_exp_f32_e32 v67, v67
	v_exp_f32_e32 v68, v68
	v_exp_f32_e32 v69, v69
	s_waitcnt lgkmcnt(12)
	v_mfma_f32_32x32x16_bf16 v[34:49], v[142:145], v[88:91], v[34:49]
	v_exp_f32_e32 v70, v70
	v_exp_f32_e32 v71, v71
	v_exp_f32_e32 v72, v72
	v_exp_f32_e32 v73, v73
	v_add_u32_e32 v84, s87, v231
	ds_read_b128 v[174:177], v84
	ds_read_b128 v[170:173], v84 offset:512
	s_waitcnt lgkmcnt(12)
	v_mfma_f32_32x32x16_bf16 v[18:33], v[138:141], v[92:95], v[18:33]
	v_exp_f32_e32 v74, v74
	v_exp_f32_e32 v75, v75
	v_exp_f32_e32 v76, v76
	v_exp_f32_e32 v77, v77
	ds_read_b128 v[166:169], v84 offset:2048
	ds_read_b128 v[162:165], v84 offset:2560
	s_waitcnt lgkmcnt(12)
	v_mfma_f32_32x32x16_bf16 v[34:49], v[138:141], v[114:117], v[34:49]
	v_exp_f32_e32 v78, v78
	v_exp_f32_e32 v79, v79
	v_exp_f32_e32 v80, v80
	v_exp_f32_e32 v81, v81
	ds_read_b128 v[158:161], v84 offset:4096
	ds_read_b128 v[154:157], v84 offset:4608
	s_waitcnt lgkmcnt(12)
	v_mfma_f32_32x32x16_bf16 v[18:33], v[134:137], v[118:121], v[18:33]
	v_exp_f32_e32 v50, v50
	v_exp_f32_e32 v51, v51
	v_exp_f32_e32 v52, v52
	v_exp_f32_e32 v53, v53
	ds_read_b128 v[150:153], v84 offset:6144
	ds_read_b128 v[146:149], v84 offset:6656
	s_waitcnt lgkmcnt(12)
	v_mfma_f32_32x32x16_bf16 v[34:49], v[134:137], v[96:99], v[34:49]
	v_exp_f32_e32 v54, v54
	v_exp_f32_e32 v55, v55
	v_exp_f32_e32 v56, v56
	v_exp_f32_e32 v57, v57
	s_waitcnt lgkmcnt(10)
	v_mfma_f32_32x32x16_bf16 v[18:33], v[130:133], v[100:103], v[18:33]
	v_exp_f32_e32 v58, v58
	v_exp_f32_e32 v59, v59
	v_exp_f32_e32 v60, v60
	v_exp_f32_e32 v61, v61
	s_waitcnt lgkmcnt(8)
	v_mfma_f32_32x32x16_bf16 v[34:49], v[130:133], v[104:107], v[34:49]
	v_exp_f32_e32 v62, v62
	v_exp_f32_e32 v63, v63
	v_exp_f32_e32 v64, v64
	v_exp_f32_e32 v65, v65
	ds_read_b64_tr_b16 v[98:99], v255 offset:24576
	ds_read_b64_tr_b16 v[100:101], v255 offset:25088
	ds_read_b64_tr_b16 v[102:103], v255 offset:28672
	ds_read_b64_tr_b16 v[104:105], v255 offset:29184
	ds_read_b64_tr_b16 v[106:107], v255 offset:25600
	ds_read_b64_tr_b16 v[108:109], v255 offset:26112
	ds_read_b64_tr_b16 v[110:111], v255 offset:29696
	ds_read_b64_tr_b16 v[112:113], v255 offset:30208
	ds_read_b64_tr_b16 v[114:115], v255 offset:26624
	ds_read_b64_tr_b16 v[116:117], v255 offset:27136
	ds_read_b64_tr_b16 v[118:119], v255 offset:30720
	ds_read_b64_tr_b16 v[120:121], v255 offset:31232
	ds_read_b64_tr_b16 v[122:123], v255 offset:27648
	ds_read_b64_tr_b16 v[124:125], v255 offset:28160
	ds_read_b64_tr_b16 v[126:127], v255 offset:31744
	ds_read_b64_tr_b16 v[128:129], v255 offset:32256
	s_waitcnt lgkmcnt(14)
	v_mfma_f32_32x32x16_bf16 v[236:251], v[142:145], v[98:101], v[236:251]
	s_waitcnt lgkmcnt(12)
	v_mfma_f32_32x32x16_bf16 v[200:215], v[142:145], v[102:105], v[200:215]
	s_waitcnt lgkmcnt(10)
	v_mfma_f32_32x32x16_bf16 v[236:251], v[138:141], v[106:109], v[236:251]
	s_waitcnt lgkmcnt(8)
	v_mfma_f32_32x32x16_bf16 v[200:215], v[138:141], v[110:113], v[200:215]
	s_waitcnt lgkmcnt(6)
	v_mfma_f32_32x32x16_bf16 v[236:251], v[134:137], v[114:117], v[236:251]
	s_waitcnt lgkmcnt(4)
	v_mfma_f32_32x32x16_bf16 v[200:215], v[134:137], v[118:121], v[200:215]
	s_waitcnt lgkmcnt(2)
	v_mfma_f32_32x32x16_bf16 v[236:251], v[130:133], v[122:125], v[236:251]
	s_waitcnt lgkmcnt(0)
	v_mfma_f32_32x32x16_bf16 v[200:215], v[130:133], v[126:129], v[200:215]
	s_sub_i32 s66, s49, 64
	v_cvt_f32_u32_e32 v84, s66
	v_mov_b32_e32 v185, v184
	s_mov_b64 s[66:67], -1
	s_and_b64 vcc, exec, s[64:65]
	v_fma_f32 v84, v184, v84, v186
	v_sub_f32_e32 v84, v84, v225
	v_fma_f32 v114, 0, v184, v84
	v_add_f32_e32 v115, v184, v84
	v_fma_f32 v117, v191, s9, v84
	v_fma_f32 v116, v190, s8, v84
	v_fma_f32 v119, v191, s11, v84
	v_fma_f32 v118, v190, s10, v84
	v_fma_f32 v121, v191, s13, v84
	v_fma_f32 v120, v190, s12, v84
	v_fma_f32 v123, v191, s15, v84
	v_fma_f32 v122, v190, s14, v84
	v_fma_f32 v125, v191, s17, v84
	v_fma_f32 v124, v190, s16, v84
	v_fma_f32 v127, v191, s19, v84
	v_fma_f32 v126, v190, s18, v84
	v_fma_f32 v129, v191, s21, v84
	v_fma_f32 v128, v190, s20, v84
	v_fma_f32 v113, v185, s23, v84
	v_fma_f32 v112, v184, s22, v84
	v_fma_f32 v111, v185, s25, v84
	v_fma_f32 v110, v184, s24, v84
	v_fma_f32 v109, v185, s27, v84
	v_fma_f32 v108, v184, s26, v84
	v_fma_f32 v107, v185, s29, v84
	v_fma_f32 v106, v184, s28, v84
	v_fma_f32 v105, v185, s31, v84
	v_fma_f32 v104, v184, s30, v84
	v_fma_f32 v103, v185, s35, v84
	v_fma_f32 v102, v184, s34, v84
	v_fma_f32 v101, v185, s37, v84
	v_fma_f32 v100, v184, s36, v84
	v_fma_f32 v99, v189, s93, v84
	v_fma_f32 v98, v188, s92, v84
	s_nop 0
	s_cbranch_vccnz .LBB0_520
	s_andn2_b64 vcc, exec, s[66:67]
	s_cbranch_vccz .LBB0_525

.LBB0_514:
	s_waitcnt lgkmcnt(4)
	v_mfma_f32_32x32x16_bf16 v[34:49], v[134:137], v[66:69], v[34:49]
	v_exp_f32_e32 v102, v102
	v_exp_f32_e32 v103, v103
	v_exp_f32_e32 v104, v104
	v_exp_f32_e32 v105, v105
	s_waitcnt lgkmcnt(2)
	v_mfma_f32_32x32x16_bf16 v[18:33], v[130:133], v[54:57], v[18:33]
	v_exp_f32_e32 v106, v106
	v_exp_f32_e32 v107, v107
	v_exp_f32_e32 v108, v108
	v_exp_f32_e32 v109, v109
	s_waitcnt lgkmcnt(0)
	v_mfma_f32_32x32x16_bf16 v[34:49], v[130:133], v[50:53], v[34:49]
	v_exp_f32_e32 v110, v110
	v_exp_f32_e32 v111, v111
	v_exp_f32_e32 v112, v112
	v_exp_f32_e32 v113, v113
	ds_read_b64_tr_b16 v[50:51], v255 offset:24576
	ds_read_b64_tr_b16 v[52:53], v255 offset:25088
	ds_read_b64_tr_b16 v[54:55], v255 offset:28672
	ds_read_b64_tr_b16 v[56:57], v255 offset:29184
	ds_read_b64_tr_b16 v[58:59], v255 offset:25600
	ds_read_b64_tr_b16 v[60:61], v255 offset:26112
	ds_read_b64_tr_b16 v[62:63], v255 offset:29696
	ds_read_b64_tr_b16 v[64:65], v255 offset:30208
	ds_read_b64_tr_b16 v[66:67], v255 offset:26624
	ds_read_b64_tr_b16 v[68:69], v255 offset:27136
	ds_read_b64_tr_b16 v[70:71], v255 offset:30720
	ds_read_b64_tr_b16 v[72:73], v255 offset:31232
	ds_read_b64_tr_b16 v[74:75], v255 offset:27648
	ds_read_b64_tr_b16 v[76:77], v255 offset:28160
	ds_read_b64_tr_b16 v[78:79], v255 offset:31744
	ds_read_b64_tr_b16 v[80:81], v255 offset:32256
	s_waitcnt lgkmcnt(14)
	v_mfma_f32_32x32x16_bf16 v[236:251], v[142:145], v[50:53], v[236:251]
	s_waitcnt lgkmcnt(12)
	v_mfma_f32_32x32x16_bf16 v[200:215], v[142:145], v[54:57], v[200:215]
	s_waitcnt lgkmcnt(10)
	v_mfma_f32_32x32x16_bf16 v[236:251], v[138:141], v[58:61], v[236:251]
	s_waitcnt lgkmcnt(8)
	v_mfma_f32_32x32x16_bf16 v[200:215], v[138:141], v[62:65], v[200:215]
	s_waitcnt lgkmcnt(6)
	v_mfma_f32_32x32x16_bf16 v[236:251], v[134:137], v[66:69], v[236:251]
	s_waitcnt lgkmcnt(4)
	v_mfma_f32_32x32x16_bf16 v[200:215], v[134:137], v[70:73], v[200:215]
	s_waitcnt lgkmcnt(2)
	v_mfma_f32_32x32x16_bf16 v[236:251], v[130:133], v[74:77], v[236:251]
	s_waitcnt lgkmcnt(0)
	v_mfma_f32_32x32x16_bf16 v[200:215], v[130:133], v[78:81], v[200:215]
	v_cvt_f32_i32_e32 v50, s49
	v_mov_b32_e32 v185, v184
	s_mov_b64 s[44:45], -1
	s_and_b64 vcc, exec, s[66:67]
	v_fma_f32 v50, v184, v50, v186
	v_sub_f32_e32 v50, v50, v225
	v_fma_f32 v66, 0, v184, v50
	v_add_f32_e32 v67, v184, v50
	v_fma_f32 v69, v191, s9, v50
	v_fma_f32 v68, v190, s8, v50
	v_fma_f32 v71, v191, s11, v50
	v_fma_f32 v70, v190, s10, v50
	v_fma_f32 v73, v191, s13, v50
	v_fma_f32 v72, v190, s12, v50
	v_fma_f32 v75, v191, s15, v50
	v_fma_f32 v74, v190, s14, v50
	v_fma_f32 v77, v191, s17, v50
	v_fma_f32 v76, v190, s16, v50
	v_fma_f32 v79, v191, s19, v50
	v_fma_f32 v78, v190, s18, v50
	v_fma_f32 v81, v191, s21, v50
	v_fma_f32 v80, v190, s20, v50
	v_fma_f32 v65, v185, s23, v50
	v_fma_f32 v64, v184, s22, v50
	v_fma_f32 v63, v185, s25, v50
	v_fma_f32 v62, v184, s24, v50
	v_fma_f32 v61, v185, s27, v50
	v_fma_f32 v60, v184, s26, v50
	v_fma_f32 v59, v185, s29, v50
	v_fma_f32 v58, v184, s28, v50
	v_fma_f32 v57, v185, s31, v50
	v_fma_f32 v56, v184, s30, v50
	v_fma_f32 v55, v185, s35, v50
	v_fma_f32 v54, v184, s34, v50
	v_fma_f32 v53, v185, s37, v50
	v_fma_f32 v52, v184, s36, v50
	v_fma_f32 v51, v189, s93, v50
	v_fma_f32 v50, v188, s92, v50
	s_nop 0
	s_cbranch_vccnz .LBB0_526
	s_andn2_b64 vcc, exec, s[44:45]
	s_cbranch_vccz .LBB0_531

; __global__ void __launch_bounds__(NWAVES * 64, 2) mk_fwd(Args args) {
	.amdhsa_kernel _Z6mk_fwd4Args
		.amdhsa_group_segment_fixed_size 0
		.amdhsa_private_segment_fixed_size 0
		.amdhsa_kernarg_size 384
		.amdhsa_user_sgpr_count 2
		.amdhsa_user_sgpr_dispatch_ptr 0
		.amdhsa_user_sgpr_queue_ptr 0
		.amdhsa_user_sgpr_kernarg_segment_ptr 1
		.amdhsa_user_sgpr_dispatch_id 0
		.amdhsa_user_sgpr_kernarg_preload_length 0
		.amdhsa_user_sgpr_kernarg_preload_offset 0
		.amdhsa_user_sgpr_private_segment_size 0
		.amdhsa_uses_dynamic_stack 0
		.amdhsa_enable_private_segment 0
		.amdhsa_system_sgpr_workgroup_id_x 1
		.amdhsa_system_sgpr_workgroup_id_y 0
		.amdhsa_system_sgpr_workgroup_id_z 0
		.amdhsa_system_sgpr_workgroup_info 0
		.amdhsa_system_vgpr_workitem_id 2
		.amdhsa_next_free_vgpr 256
		.amdhsa_next_free_sgpr 102
		.amdhsa_accum_offset 256
		.amdhsa_reserve_vcc 1
		.amdhsa_float_round_mode_32 0
		.amdhsa_float_round_mode_16_64 0
		.amdhsa_float_denorm_mode_32 3
		.amdhsa_float_denorm_mode_16_64 3
		.amdhsa_dx10_clamp 1
		.amdhsa_ieee_mode 1
		.amdhsa_fp16_overflow 0
		.amdhsa_tg_split 0
		.amdhsa_exception_fp_ieee_invalid_op 0
		.amdhsa_exception_fp_denorm_src 0
		.amdhsa_exception_fp_ieee_div_zero 0
		.amdhsa_exception_fp_ieee_overflow 0
		.amdhsa_exception_fp_ieee_underflow 0
		.amdhsa_exception_fp_ieee_inexact 0
		.amdhsa_exception_int_div_zero 0
	.end_amdhsa_kernel

; __global__ void __launch_bounds__(NWAVES * 64, 2) mk_fwd(Args args) {
amdhsa.kernels:
  - .agpr_count:     0
    .args:
      - .offset:         0
        .size:           128
        .value_kind:     by_value
      - .offset:         128
        .size:           4
        .value_kind:     hidden_block_count_x
      - .offset:         132
        .size:           4
        .value_kind:     hidden_block_count_y
      - .offset:         136
        .size:           4
        .value_kind:     hidden_block_count_z
      - .offset:         140
        .size:           2
        .value_kind:     hidden_group_size_x
      - .offset:         142
        .size:           2
        .value_kind:     hidden_group_size_y
      - .offset:         144
        .size:           2
        .value_kind:     hidden_group_size_z
      - .offset:         146
        .size:           2
        .value_kind:     hidden_remainder_x
      - .offset:         148
        .size:           2
        .value_kind:     hidden_remainder_y
      - .offset:         150
        .size:           2
        .value_kind:     hidden_remainder_z
      - .offset:         168
        .size:           8
        .value_kind:     hidden_global_offset_x
      - .offset:         176
        .size:           8
        .value_kind:     hidden_global_offset_y
      - .offset:         184
        .size:           8
        .value_kind:     hidden_global_offset_z
      - .offset:         192
        .size:           2
        .value_kind:     hidden_grid_dims
      - .offset:         216
        .size:           8
        .value_kind:     hidden_multigrid_sync_arg
      - .offset:         248
        .size:           4
        .value_kind:     hidden_dynamic_lds_size
    .group_segment_fixed_size: 0
    .kernarg_segment_align: 8
    .kernarg_segment_size: 384
    .language:       OpenCL C
    .language_version:
      - 2
      - 0
    .max_flat_workgroup_size: 512
    .name:           _Z6mk_fwd4Args
    .private_segment_fixed_size: 0
    .sgpr_count:     108
    .sgpr_spill_count: 155
    .symbol:         _Z6mk_fwd4Args.kd
    .uniform_work_group_size: 1
    .uses_dynamic_stack: false
    .vgpr_count:     256
    .vgpr_spill_count: 0
    .wavefront_size: 64
